# nt hint also on the phase-0 stores of the late-use weight copies (gate_up2, down2, w_in, w_mem_kv, w_out); on top of m7
# speedup vs baseline: 1.0043x; 1.0043x over previous
; #define LAS __attribute__((address_space(3)))
; #define SCHED_FENCE() __builtin_amdgcn_sched_barrier(0)
; __device__ __forceinline__ void transpose_item(const float* W, int K, int N, bf16_t* WT, int kb, int nbd, int src0, LAS float* scr, int lane, const float* gk = nullptr) {
;     const int k0 = kb * 64;
;     const float* wp = W + (size_t)(k0 + (lane >> 4)) * N + src0 + (lane & 15) * 4;
;     f32x4 v[16];
; #pragma unroll
;     for (int i = 0; i < 16; ++i) v[i] = *(const f32x4*)(wp + (size_t)(4 * i) * N);
;     SCHED_FENCE();
; #pragma unroll
;     for (int i = 0; i < 16; ++i) { if (gk) v[i] = v[i] * gk[k0 + 4 * i + (lane >> 4)];
;         LAS float* s = scr + (4 * i + (lane >> 4)) * 65 + (lane & 15) * 4; s[0] = v[i].x; s[1] = v[i].y; s[2] = v[i].z; s[3] = v[i].w; }
; __global__ void __launch_bounds__(512, 2) fwd_kernel(Args a) {
;     ...
;             for (int it = gw; it < NITEMS; it += ngw) {
;                 int r = it;
;                 if (r < I_GU) { const int nb = r % 176; transpose_item(P.in[3], DM, NGU, (bf16_t*)(ws + WS_WGU1), r / 176, nb, map_gu(nb), scr, lane, P.in[2]); continue; } r -= I_GU;
;                 if (r < I_GU) { const int nb = r % 176; transpose_item(P.in[21], DM, NGU, (bf16_t*)(ws + WS_WGU2), r / 176, nb, map_gu(nb), scr, lane, P.in[20]); continue; } r -= I_GU;
;                 if (r < I_D) { const int nb = r % 32; transpose_item(P.in[4], DFF, DM, (bf16_t*)(ws + WS_WD1), r / 32, nb, nb * 64, scr, lane); continue; } r -= I_D;
;                 if (r < I_D) { const int nb = r % 32; transpose_item(P.in[22], DFF, DM, (bf16_t*)(ws + WS_WD2), r / 32, nb, nb * 64, scr, lane); continue; } r -= I_D;
;                 if (r < I_IN) { const int nb = r % 72; transpose_item(P.in[8], DM, 4608, (bf16_t*)(ws + WS_WIN), r / 72, nb, map_win(nb), scr, lane, P.in[6]); continue; } r -= I_IN;
;                 if (r < I_MKV) { const int nb = r % 16; transpose_item(P.in[9], DM, 1024, (bf16_t*)(ws + WS_WMKV), r / 16, nb, nb * 64, scr, lane); continue; } r -= I_MKV;
;                 { const int nb = r % 32; transpose_item(P.in[18], DM, DM, (bf16_t*)(ws + WS_WOUT), r / 32, nb, nb * 64, scr, lane); }
.Lmap_done:
	s_lshl_b32 s10, s28, 5
	s_lshl_b32 s23, s28, 6
	s_lshl_b32 s13, s28, 1
	s_lshl_b32 s19, s28, 2
	s_cmpk_gt_i32 s28, 0x15ff
	s_mov_b64 s[6:7], -1
	s_cbranch_scc0 .LBB0_337
	s_cmpk_gt_u32 s28, 0x2bff
	s_cbranch_scc0 .LBB0_310
	s_cmpk_gt_u32 s28, 0x36ff
	s_cbranch_scc0 .LBB0_307
	s_cmpk_gt_u32 s28, 0x41ff
	s_cbranch_scc0 .LBB0_304
	s_cmpk_gt_u32 s28, 0x4aff
	s_cbranch_scc0 .LBB0_268
	s_cmpk_gt_u32 s28, 0x4cff
	s_cbranch_scc0 .LBB0_265
	s_load_dwordx2 s[30:31], s[40:41], 0x90
	s_and_b32 s6, s13, 0x7fffffc0
	s_add_i32 s6, s6, 0xffff6600
	v_or_b32_e32 v144, s6, v92
	s_and_b32 s8, s23, 0x7c0
	v_lshlrev_b64 v[0:1], 13, v[144:145]
	s_waitcnt lgkmcnt(0)
	v_lshl_add_u64 v[0:1], s[30:31], 0, v[0:1]
	s_lshl_b32 s74, s8, 2
	v_lshl_add_u64 v[0:1], v[0:1], 0, s[74:75]
	v_lshlrev_b32_e32 v144, 2, v70
	v_lshl_add_u64 v[56:57], v[0:1], 0, v[144:145]
	v_add_co_u32_e32 v4, vcc, 0x8000, v56
	s_mov_b32 s0, 0x18000
	s_nop 0
	v_addc_co_u32_e32 v5, vcc, 0, v57, vcc
	v_add_co_u32_e32 v8, vcc, s47, v56
	global_load_dwordx4 v[0:3], v[56:57], off nt
	s_nop 0
	global_load_dwordx4 v[4:7], v[4:5], off nt
	v_addc_co_u32_e32 v9, vcc, 0, v57, vcc
	v_add_co_u32_e32 v12, vcc, s0, v56
	s_mov_b32 s0, 0x48000
	s_nop 0
	v_addc_co_u32_e32 v13, vcc, 0, v57, vcc
	v_add_co_u32_e32 v16, vcc, 0x20000, v56
	global_load_dwordx4 v[8:11], v[8:9], off nt
	s_nop 0
	global_load_dwordx4 v[12:15], v[12:13], off nt
	v_addc_co_u32_e32 v17, vcc, 0, v57, vcc
	v_add_co_u32_e32 v20, vcc, 0x28000, v56
	s_nop 1
	v_addc_co_u32_e32 v21, vcc, 0, v57, vcc
	v_add_co_u32_e32 v24, vcc, s3, v56
	global_load_dwordx4 v[16:19], v[16:17], off nt
	s_nop 0
	global_load_dwordx4 v[20:23], v[20:21], off nt
	v_addc_co_u32_e32 v25, vcc, 0, v57, vcc
	v_add_co_u32_e32 v28, vcc, 0x38000, v56
	s_nop 1
	v_addc_co_u32_e32 v29, vcc, 0, v57, vcc
	v_add_co_u32_e32 v32, vcc, s21, v56
	global_load_dwordx4 v[24:27], v[24:25], off nt
	s_nop 0
	global_load_dwordx4 v[28:31], v[28:29], off nt
	v_addc_co_u32_e32 v33, vcc, 0, v57, vcc
	v_add_co_u32_e32 v36, vcc, s0, v56
	s_mov_b32 s0, 0x58000
	s_nop 0
	v_addc_co_u32_e32 v37, vcc, 0, v57, vcc
	v_add_co_u32_e32 v40, vcc, s20, v56
	global_load_dwordx4 v[32:35], v[32:33], off nt
	s_nop 0
	global_load_dwordx4 v[36:39], v[36:37], off nt
	v_addc_co_u32_e32 v41, vcc, 0, v57, vcc
	v_add_co_u32_e32 v44, vcc, s0, v56
	s_mov_b32 s0, 0x68000
	s_nop 0
	v_addc_co_u32_e32 v45, vcc, 0, v57, vcc
	v_add_co_u32_e32 v48, vcc, s26, v56
	global_load_dwordx4 v[40:43], v[40:41], off nt
	s_nop 0
	global_load_dwordx4 v[44:47], v[44:45], off nt
	v_addc_co_u32_e32 v49, vcc, 0, v57, vcc
	v_add_co_u32_e32 v52, vcc, s0, v56
	s_mov_b32 s0, 0x78000
	s_nop 0
	v_addc_co_u32_e32 v53, vcc, 0, v57, vcc
	v_add_co_u32_e32 v58, vcc, s48, v56
	global_load_dwordx4 v[48:51], v[48:49], off nt
	s_nop 0
	global_load_dwordx4 v[52:55], v[52:53], off nt
	v_addc_co_u32_e32 v59, vcc, 0, v57, vcc
	v_add_co_u32_e32 v60, vcc, s0, v56
	s_nop 1
	v_addc_co_u32_e32 v61, vcc, 0, v57, vcc
	global_load_dwordx4 v[56:59], v[58:59], off nt
	s_nop 0
	global_load_dwordx4 v[60:63], v[60:61], off nt
	s_waitcnt vmcnt(15)
	ds_write2_b32 v93, v0, v1 offset1:1
	ds_write2_b32 v93, v2, v3 offset0:2 offset1:3
	v_add_u32_e32 v0, 0x410, v93
	s_waitcnt vmcnt(14)
	ds_write2_b32 v0, v4, v5 offset1:1
	v_add_u32_e32 v0, 0x418, v93
	ds_write2_b32 v0, v6, v7 offset1:1
	v_add_u32_e32 v0, 0x820, v93
	s_waitcnt vmcnt(13)
	ds_write2_b32 v0, v8, v9 offset1:1
	v_add_u32_e32 v0, 0x828, v93
	ds_write2_b32 v0, v10, v11 offset1:1
	v_add_u32_e32 v0, 0xc30, v93
	s_waitcnt vmcnt(12)
	ds_write2_b32 v0, v12, v13 offset1:1
	v_add_u32_e32 v0, 0xc38, v93
	ds_write2_b32 v0, v14, v15 offset1:1
	v_add_u32_e32 v0, 0x1040, v93
	s_waitcnt vmcnt(11)
	ds_write2_b32 v0, v16, v17 offset1:1
	v_add_u32_e32 v0, 0x1048, v93
	ds_write2_b32 v0, v18, v19 offset1:1
	v_add_u32_e32 v0, 0x1450, v93
	s_waitcnt vmcnt(10)
	ds_write2_b32 v0, v20, v21 offset1:1
	v_add_u32_e32 v0, 0x1458, v93
	ds_write2_b32 v0, v22, v23 offset1:1
	v_add_u32_e32 v0, 0x1860, v93
	s_waitcnt vmcnt(9)
	ds_write2_b32 v0, v24, v25 offset1:1
	v_add_u32_e32 v0, 0x1868, v93
	ds_write2_b32 v0, v26, v27 offset1:1
	v_add_u32_e32 v0, 0x1c70, v93
	s_waitcnt vmcnt(8)
	ds_write2_b32 v0, v28, v29 offset1:1
	v_add_u32_e32 v0, 0x1c78, v93
	ds_write2_b32 v0, v30, v31 offset1:1
	v_add_u32_e32 v0, 0x2080, v93
	s_waitcnt vmcnt(7)
	ds_write2_b32 v0, v32, v33 offset1:1
	v_add_u32_e32 v0, 0x2088, v93
	ds_write2_b32 v0, v34, v35 offset1:1
	v_add_u32_e32 v0, 0x2490, v93
	s_waitcnt vmcnt(6)
	ds_write2_b32 v0, v36, v37 offset1:1
	v_add_u32_e32 v0, 0x2498, v93
	ds_write2_b32 v0, v38, v39 offset1:1
	v_add_u32_e32 v0, 0x28a0, v93
	s_waitcnt vmcnt(5)
	ds_write2_b32 v0, v40, v41 offset1:1
	v_add_u32_e32 v0, 0x28a8, v93
	ds_write2_b32 v0, v42, v43 offset1:1
	v_add_u32_e32 v0, 0x2cb0, v93
	s_waitcnt vmcnt(4)
	ds_write2_b32 v0, v44, v45 offset1:1
	v_add_u32_e32 v0, 0x2cb8, v93
	ds_write2_b32 v0, v46, v47 offset1:1
	v_add_u32_e32 v0, 0x30c0, v93
	s_waitcnt vmcnt(3)
	ds_write2_b32 v0, v48, v49 offset1:1
	v_add_u32_e32 v0, 0x30c8, v93
	ds_write2_b32 v0, v50, v51 offset1:1
	v_add_u32_e32 v0, 0x34d0, v93
	s_waitcnt vmcnt(2)
	ds_write2_b32 v0, v52, v53 offset1:1
	v_add_u32_e32 v0, 0x34d8, v93
	ds_write2_b32 v0, v54, v55 offset1:1
	v_add_u32_e32 v0, 0x38e0, v93
	s_waitcnt vmcnt(1)
	ds_write2_b32 v0, v56, v57 offset1:1
	v_add_u32_e32 v0, 0x38e8, v93
	ds_write2_b32 v0, v58, v59 offset1:1
	v_add_u32_e32 v0, 0x3cf0, v93
	s_waitcnt vmcnt(0)
; #define LAS __attribute__((address_space(3)))
; __device__ __forceinline__ unsigned pk2(float lo, float hi) { unsigned r; asm("v_cvt_pk_bf16_f32 %0, %1, %2" : "=v"(r) : "v"(lo), "v"(hi)); return r; }
; __device__ __forceinline__ void transpose_item(const float* W, int K, int N, bf16_t* WT, int kb, int nbd, int src0, LAS float* scr, int lane, const float* gk = nullptr) {
;     ...
;     const int c = lane & 7;
; #pragma unroll
;     for (int jj = 0; jj < 8; ++jj) {
;         const int n = (lane >> 3) + 8 * jj; const LAS float* s = scr + (8 * c) * 65 + n;
;         u32x4 o; o.x = pk2(s[0], s[65]); o.y = pk2(s[2 * 65], s[3 * 65]); o.z = pk2(s[4 * 65], s[5 * 65]); o.w = pk2(s[6 * 65], s[7 * 65]);
;         *(u32x4*)(WT + (size_t)(nbd * 64 + n) * K + k0 + 8 * c) = o;
;     }
	ds_write2_b32 v0, v60, v61 offset1:1
	v_add_u32_e32 v0, 0x3cf8, v93
	ds_write2_b32 v0, v62, v63 offset1:1
	ds_read2_b32 v[4:5], v95 offset0:65 offset1:73
	ds_read2_b32 v[6:7], v95 offset1:8
	ds_read2_b32 v[8:9], v95 offset0:130 offset1:138
	ds_read2_b32 v[10:11], v95 offset0:195 offset1:203
	v_add_u32_e32 v24, 0x400, v95
	ds_read2_b32 v[12:13], v24 offset0:4 offset1:12
	ds_read2_b32 v[14:15], v24 offset0:69 offset1:77
	ds_read2_b32 v[16:17], v24 offset0:134 offset1:142
	ds_read2_b32 v[18:19], v24 offset0:199 offset1:207
	s_mov_b32 s7, s75
	s_waitcnt lgkmcnt(6)
	v_cvt_pk_bf16_f32 v0, v6, v4
	v_or_b32_e32 v4, s8, v94
	v_lshl_add_u64 v[20:21], s[6:7], 1, v[72:73]
	v_lshlrev_b32_e32 v144, 12, v4
	v_lshl_add_u64 v[22:23], v[20:21], 0, v[144:145]
	s_waitcnt lgkmcnt(4)
	v_cvt_pk_bf16_f32 v1, v8, v10
	s_waitcnt lgkmcnt(2)
	v_cvt_pk_bf16_f32 v2, v12, v14
	s_waitcnt lgkmcnt(0)
	v_cvt_pk_bf16_f32 v3, v16, v18
	global_store_dwordx4 v[22:23], v[0:3], off nt
	v_or_b32_e32 v4, s8, v96
	v_lshlrev_b32_e32 v144, 12, v4
	v_cvt_pk_bf16_f32 v0, v7, v5
	v_cvt_pk_bf16_f32 v1, v9, v11
	v_cvt_pk_bf16_f32 v2, v13, v15
	v_cvt_pk_bf16_f32 v3, v17, v19
	ds_read2_b32 v[6:7], v95 offset0:16 offset1:24
	ds_read2_b32 v[8:9], v95 offset0:81 offset1:89
	ds_read2_b32 v[10:11], v95 offset0:146 offset1:154
	ds_read2_b32 v[12:13], v95 offset0:211 offset1:219
	ds_read2_b32 v[14:15], v24 offset0:20 offset1:28
	ds_read2_b32 v[16:17], v24 offset0:85 offset1:93
	ds_read2_b32 v[18:19], v24 offset0:150 offset1:158
	ds_read2_b32 v[22:23], v24 offset0:215 offset1:223
	v_lshl_add_u64 v[4:5], v[20:21], 0, v[144:145]
	global_store_dwordx4 v[4:5], v[0:3], off nt
	v_or_b32_e32 v4, s8, v97
	v_lshlrev_b32_e32 v144, 12, v4
	v_lshl_add_u64 v[4:5], v[20:21], 0, v[144:145]
	s_waitcnt lgkmcnt(6)
	v_cvt_pk_bf16_f32 v0, v6, v8
	s_waitcnt lgkmcnt(4)
	v_cvt_pk_bf16_f32 v1, v10, v12
	s_waitcnt lgkmcnt(2)
	v_cvt_pk_bf16_f32 v2, v14, v16
	s_waitcnt lgkmcnt(0)
	v_cvt_pk_bf16_f32 v3, v18, v22
	global_store_dwordx4 v[4:5], v[0:3], off nt
	v_or_b32_e32 v4, s8, v98
	v_lshlrev_b32_e32 v144, 12, v4
	v_cvt_pk_bf16_f32 v0, v7, v9
	v_cvt_pk_bf16_f32 v1, v11, v13
	v_cvt_pk_bf16_f32 v2, v15, v17
	v_cvt_pk_bf16_f32 v3, v19, v23
	ds_read2_b32 v[6:7], v95 offset0:32 offset1:40
	ds_read2_b32 v[8:9], v95 offset0:97 offset1:105
	ds_read2_b32 v[10:11], v95 offset0:162 offset1:170
	ds_read2_b32 v[12:13], v95 offset0:227 offset1:235
	ds_read2_b32 v[14:15], v24 offset0:36 offset1:44
	ds_read2_b32 v[16:17], v24 offset0:101 offset1:109
	ds_read2_b32 v[18:19], v24 offset0:166 offset1:174
	ds_read2_b32 v[22:23], v24 offset0:231 offset1:239
	v_lshl_add_u64 v[4:5], v[20:21], 0, v[144:145]
	global_store_dwordx4 v[4:5], v[0:3], off nt
	v_or_b32_e32 v4, s8, v99
	v_lshlrev_b32_e32 v144, 12, v4
	v_lshl_add_u64 v[4:5], v[20:21], 0, v[144:145]
	s_waitcnt lgkmcnt(6)
	v_cvt_pk_bf16_f32 v0, v6, v8
	s_waitcnt lgkmcnt(4)
	v_cvt_pk_bf16_f32 v1, v10, v12
	s_waitcnt lgkmcnt(2)
	v_cvt_pk_bf16_f32 v2, v14, v16
	s_waitcnt lgkmcnt(0)
	v_cvt_pk_bf16_f32 v3, v18, v22
	global_store_dwordx4 v[4:5], v[0:3], off nt
	v_or_b32_e32 v4, s8, v100
	v_lshlrev_b32_e32 v144, 12, v4
	v_cvt_pk_bf16_f32 v0, v7, v9
	v_cvt_pk_bf16_f32 v1, v11, v13
	v_cvt_pk_bf16_f32 v2, v15, v17
	v_cvt_pk_bf16_f32 v3, v19, v23
	ds_read2_b32 v[6:7], v95 offset0:48 offset1:56
	ds_read2_b32 v[8:9], v95 offset0:113 offset1:121
	ds_read2_b32 v[10:11], v95 offset0:178 offset1:186
	ds_read2_b32 v[12:13], v95 offset0:243 offset1:251
	ds_read2_b32 v[14:15], v24 offset0:52 offset1:60
	ds_read2_b32 v[16:17], v24 offset0:117 offset1:125
	ds_read2_b32 v[18:19], v24 offset0:182 offset1:190
	ds_read2_b32 v[22:23], v24 offset0:247 offset1:255
	v_lshl_add_u64 v[4:5], v[20:21], 0, v[144:145]
	global_store_dwordx4 v[4:5], v[0:3], off nt
	v_or_b32_e32 v4, s8, v101
	v_lshlrev_b32_e32 v144, 12, v4
	v_lshl_add_u64 v[4:5], v[20:21], 0, v[144:145]
	s_waitcnt lgkmcnt(6)
	v_cvt_pk_bf16_f32 v0, v6, v8
	s_waitcnt lgkmcnt(4)
	v_cvt_pk_bf16_f32 v1, v10, v12
	s_waitcnt lgkmcnt(2)
	v_cvt_pk_bf16_f32 v2, v14, v16
	s_waitcnt lgkmcnt(0)
	v_cvt_pk_bf16_f32 v3, v18, v22
	global_store_dwordx4 v[4:5], v[0:3], off nt
	v_or_b32_e32 v4, s8, v102
	v_lshlrev_b32_e32 v144, 12, v4
	v_lshl_add_u64 v[4:5], v[20:21], 0, v[144:145]
	v_cvt_pk_bf16_f32 v0, v7, v9
	v_cvt_pk_bf16_f32 v1, v11, v13
	v_cvt_pk_bf16_f32 v2, v15, v17
	v_cvt_pk_bf16_f32 v3, v19, v23
	global_store_dwordx4 v[4:5], v[0:3], off nt
	s_mov_b64 s[6:7], 0
; #define LAS __attribute__((address_space(3)))
; #define SCHED_FENCE() __builtin_amdgcn_sched_barrier(0)
; __device__ __forceinline__ void transpose_item(const float* W, int K, int N, bf16_t* WT, int kb, int nbd, int src0, LAS float* scr, int lane, const float* gk = nullptr) {
;     const int k0 = kb * 64;
;     const float* wp = W + (size_t)(k0 + (lane >> 4)) * N + src0 + (lane & 15) * 4;
;     f32x4 v[16];
; #pragma unroll
;     for (int i = 0; i < 16; ++i) v[i] = *(const f32x4*)(wp + (size_t)(4 * i) * N);
;     SCHED_FENCE();
; #pragma unroll
;     for (int i = 0; i < 16; ++i) { if (gk) v[i] = v[i] * gk[k0 + 4 * i + (lane >> 4)];
;         LAS float* s = scr + (4 * i + (lane >> 4)) * 65 + (lane & 15) * 4; s[0] = v[i].x; s[1] = v[i].y; s[2] = v[i].z; s[3] = v[i].w; }
.LBB0_265:
	s_andn2_b64 vcc, exec, s[6:7]
	s_cbranch_vccnz .LBB0_267
	s_and_b32 s6, s19, 0x1ffc0
	s_add_i32 s6, s6, 0xfffed400
	v_or_b32_e32 v144, s6, v92
	v_readlane_b32 s80, v252, 0
	s_and_b32 s8, s23, 0x3c0
	v_lshlrev_b64 v[0:1], 12, v[144:145]
	v_readlane_b32 s86, v252, 6
	v_readlane_b32 s87, v252, 7
	s_lshl_b32 s74, s8, 2
	v_lshlrev_b32_e32 v144, 2, v70
	v_lshl_add_u64 v[0:1], s[86:87], 0, v[0:1]
	v_lshl_add_u64 v[0:1], v[0:1], 0, s[74:75]
	v_lshl_add_u64 v[56:57], v[0:1], 0, v[144:145]
	v_add_co_u32_e32 v4, vcc, 0x4000, v56
	s_mov_b32 s7, 0x38000
	s_waitcnt lgkmcnt(0)
	v_addc_co_u32_e32 v5, vcc, 0, v57, vcc
	v_add_co_u32_e32 v8, vcc, 0x8000, v56
	global_load_dwordx4 v[0:3], v[56:57], off nt
	s_nop 0
	global_load_dwordx4 v[4:7], v[4:5], off nt
	v_addc_co_u32_e32 v9, vcc, 0, v57, vcc
	v_add_co_u32_e32 v12, vcc, 0xc000, v56
	v_readlane_b32 s81, v252, 1
	s_nop 0
	v_addc_co_u32_e32 v13, vcc, 0, v57, vcc
	v_add_co_u32_e32 v16, vcc, 0x10000, v56
	global_load_dwordx4 v[8:11], v[8:9], off nt
	s_nop 0
	global_load_dwordx4 v[12:15], v[12:13], off nt
	v_addc_co_u32_e32 v17, vcc, 0, v57, vcc
	v_add_co_u32_e32 v20, vcc, 0x14000, v56
	v_readlane_b32 s82, v252, 2
	s_nop 0
	v_addc_co_u32_e32 v21, vcc, 0, v57, vcc
	v_add_co_u32_e32 v24, vcc, 0x18000, v56
	global_load_dwordx4 v[16:19], v[16:17], off nt
	s_nop 0
	global_load_dwordx4 v[20:23], v[20:21], off nt
	v_addc_co_u32_e32 v25, vcc, 0, v57, vcc
	v_add_co_u32_e32 v28, vcc, 0x1c000, v56
	v_readlane_b32 s83, v252, 3
	s_nop 0
	v_addc_co_u32_e32 v29, vcc, 0, v57, vcc
	v_add_co_u32_e32 v32, vcc, 0x20000, v56
	global_load_dwordx4 v[24:27], v[24:25], off nt
	s_nop 0
	global_load_dwordx4 v[28:31], v[28:29], off nt
	v_addc_co_u32_e32 v33, vcc, 0, v57, vcc
	v_add_co_u32_e32 v36, vcc, 0x24000, v56
	v_readlane_b32 s84, v252, 4
	s_waitcnt lgkmcnt(0)
	v_addc_co_u32_e32 v37, vcc, 0, v57, vcc
	v_add_co_u32_e32 v40, vcc, 0x28000, v56
	global_load_dwordx4 v[32:35], v[32:33], off nt
	s_nop 0
	global_load_dwordx4 v[36:39], v[36:37], off nt
	v_addc_co_u32_e32 v41, vcc, 0, v57, vcc
	v_add_co_u32_e32 v44, vcc, 0x2c000, v56
	v_readlane_b32 s85, v252, 5
	s_nop 0
	v_addc_co_u32_e32 v45, vcc, 0, v57, vcc
	v_add_co_u32_e32 v48, vcc, s3, v56
	global_load_dwordx4 v[40:43], v[40:41], off nt
	s_nop 0
	global_load_dwordx4 v[44:47], v[44:45], off nt
	v_addc_co_u32_e32 v49, vcc, 0, v57, vcc
	v_add_co_u32_e32 v52, vcc, 0x34000, v56
	v_readlane_b32 s88, v252, 8
	s_nop 0
	v_addc_co_u32_e32 v53, vcc, 0, v57, vcc
	v_add_co_u32_e32 v58, vcc, s7, v56
	global_load_dwordx4 v[48:51], v[48:49], off nt
	s_nop 0
	global_load_dwordx4 v[52:55], v[52:53], off nt
	v_addc_co_u32_e32 v59, vcc, 0, v57, vcc
	v_add_co_u32_e32 v60, vcc, 0x3c000, v56
	v_readlane_b32 s89, v252, 9
	s_nop 0
	v_addc_co_u32_e32 v61, vcc, 0, v57, vcc
	global_load_dwordx4 v[56:59], v[58:59], off nt
	s_nop 0
	global_load_dwordx4 v[60:63], v[60:61], off nt
	v_readlane_b32 s90, v252, 10
	v_readlane_b32 s91, v252, 11
	v_readlane_b32 s92, v252, 12
	v_readlane_b32 s93, v252, 13
	v_readlane_b32 s94, v252, 14
	v_readlane_b32 s95, v252, 15
	s_waitcnt vmcnt(15)
	ds_write2_b32 v93, v0, v1 offset1:1
	ds_write2_b32 v93, v2, v3 offset0:2 offset1:3
	v_add_u32_e32 v0, 0x410, v93
	s_waitcnt vmcnt(14)
	ds_write2_b32 v0, v4, v5 offset1:1
	v_add_u32_e32 v0, 0x418, v93
	ds_write2_b32 v0, v6, v7 offset1:1
	v_add_u32_e32 v0, 0x820, v93
	s_waitcnt vmcnt(13)
	ds_write2_b32 v0, v8, v9 offset1:1
	v_add_u32_e32 v0, 0x828, v93
	ds_write2_b32 v0, v10, v11 offset1:1
	v_add_u32_e32 v0, 0xc30, v93
	s_waitcnt vmcnt(12)
	ds_write2_b32 v0, v12, v13 offset1:1
	v_add_u32_e32 v0, 0xc38, v93
	ds_write2_b32 v0, v14, v15 offset1:1
	v_add_u32_e32 v0, 0x1040, v93
	s_waitcnt vmcnt(11)
	ds_write2_b32 v0, v16, v17 offset1:1
	v_add_u32_e32 v0, 0x1048, v93
	ds_write2_b32 v0, v18, v19 offset1:1
	v_add_u32_e32 v0, 0x1450, v93
	s_waitcnt vmcnt(10)
	ds_write2_b32 v0, v20, v21 offset1:1
	v_add_u32_e32 v0, 0x1458, v93
	ds_write2_b32 v0, v22, v23 offset1:1
	v_add_u32_e32 v0, 0x1860, v93
	s_waitcnt vmcnt(9)
	ds_write2_b32 v0, v24, v25 offset1:1
	v_add_u32_e32 v0, 0x1868, v93
	ds_write2_b32 v0, v26, v27 offset1:1
	v_add_u32_e32 v0, 0x1c70, v93
	s_waitcnt vmcnt(8)
	ds_write2_b32 v0, v28, v29 offset1:1
	v_add_u32_e32 v0, 0x1c78, v93
	ds_write2_b32 v0, v30, v31 offset1:1
	v_add_u32_e32 v0, 0x2080, v93
	s_waitcnt vmcnt(7)
	ds_write2_b32 v0, v32, v33 offset1:1
	v_add_u32_e32 v0, 0x2088, v93
	ds_write2_b32 v0, v34, v35 offset1:1
	v_add_u32_e32 v0, 0x2490, v93
	s_waitcnt vmcnt(6)
	ds_write2_b32 v0, v36, v37 offset1:1
	v_add_u32_e32 v0, 0x2498, v93
	ds_write2_b32 v0, v38, v39 offset1:1
	v_add_u32_e32 v0, 0x28a0, v93
	s_waitcnt vmcnt(5)
	ds_write2_b32 v0, v40, v41 offset1:1
	v_add_u32_e32 v0, 0x28a8, v93
	ds_write2_b32 v0, v42, v43 offset1:1
	v_add_u32_e32 v0, 0x2cb0, v93
	s_waitcnt vmcnt(4)
	ds_write2_b32 v0, v44, v45 offset1:1
	v_add_u32_e32 v0, 0x2cb8, v93
	ds_write2_b32 v0, v46, v47 offset1:1
	v_add_u32_e32 v0, 0x30c0, v93
	s_waitcnt vmcnt(3)
; #define LAS __attribute__((address_space(3)))
; __device__ __forceinline__ unsigned pk2(float lo, float hi) { unsigned r; asm("v_cvt_pk_bf16_f32 %0, %1, %2" : "=v"(r) : "v"(lo), "v"(hi)); return r; }
; __device__ __forceinline__ void transpose_item(const float* W, int K, int N, bf16_t* WT, int kb, int nbd, int src0, LAS float* scr, int lane, const float* gk = nullptr) {
;     ...
;         LAS float* s = scr + (4 * i + (lane >> 4)) * 65 + (lane & 15) * 4; s[0] = v[i].x; s[1] = v[i].y; s[2] = v[i].z; s[3] = v[i].w; }
;     const int c = lane & 7;
; #pragma unroll
;     for (int jj = 0; jj < 8; ++jj) {
;         const int n = (lane >> 3) + 8 * jj; const LAS float* s = scr + (8 * c) * 65 + n;
;         u32x4 o; o.x = pk2(s[0], s[65]); o.y = pk2(s[2 * 65], s[3 * 65]); o.z = pk2(s[4 * 65], s[5 * 65]); o.w = pk2(s[6 * 65], s[7 * 65]);
;         *(u32x4*)(WT + (size_t)(nbd * 64 + n) * K + k0 + 8 * c) = o;
;     }
	ds_write2_b32 v0, v48, v49 offset1:1
	v_add_u32_e32 v0, 0x30c8, v93
	ds_write2_b32 v0, v50, v51 offset1:1
	v_add_u32_e32 v0, 0x34d0, v93
	s_waitcnt vmcnt(2)
	ds_write2_b32 v0, v52, v53 offset1:1
	v_add_u32_e32 v0, 0x34d8, v93
	ds_write2_b32 v0, v54, v55 offset1:1
	v_add_u32_e32 v0, 0x38e0, v93
	s_waitcnt vmcnt(1)
	ds_write2_b32 v0, v56, v57 offset1:1
	v_add_u32_e32 v0, 0x38e8, v93
	ds_write2_b32 v0, v58, v59 offset1:1
	v_add_u32_e32 v0, 0x3cf0, v93
	s_waitcnt vmcnt(0)
	ds_write2_b32 v0, v60, v61 offset1:1
	v_add_u32_e32 v0, 0x3cf8, v93
	ds_write2_b32 v0, v62, v63 offset1:1
	ds_read2_b32 v[4:5], v95 offset0:65 offset1:73
	ds_read2_b32 v[6:7], v95 offset1:8
	ds_read2_b32 v[8:9], v95 offset0:130 offset1:138
	ds_read2_b32 v[10:11], v95 offset0:195 offset1:203
	v_add_u32_e32 v24, 0x400, v95
	ds_read2_b32 v[12:13], v24 offset0:4 offset1:12
	ds_read2_b32 v[14:15], v24 offset0:69 offset1:77
	ds_read2_b32 v[16:17], v24 offset0:134 offset1:142
	ds_read2_b32 v[18:19], v24 offset0:199 offset1:207
	s_mov_b32 s7, s75
	s_waitcnt lgkmcnt(6)
	v_cvt_pk_bf16_f32 v0, v6, v4
	v_or_b32_e32 v4, s8, v94
	v_lshl_add_u64 v[20:21], s[6:7], 1, v[74:75]
	v_lshlrev_b32_e32 v144, 12, v4
	v_lshl_add_u64 v[22:23], v[20:21], 0, v[144:145]
	s_waitcnt lgkmcnt(4)
	v_cvt_pk_bf16_f32 v1, v8, v10
	s_waitcnt lgkmcnt(2)
	v_cvt_pk_bf16_f32 v2, v12, v14
	s_waitcnt lgkmcnt(0)
	v_cvt_pk_bf16_f32 v3, v16, v18
	global_store_dwordx4 v[22:23], v[0:3], off nt
	v_or_b32_e32 v4, s8, v96
	v_lshlrev_b32_e32 v144, 12, v4
	v_cvt_pk_bf16_f32 v0, v7, v5
	v_cvt_pk_bf16_f32 v1, v9, v11
	v_cvt_pk_bf16_f32 v2, v13, v15
	v_cvt_pk_bf16_f32 v3, v17, v19
	ds_read2_b32 v[6:7], v95 offset0:16 offset1:24
	ds_read2_b32 v[8:9], v95 offset0:81 offset1:89
	ds_read2_b32 v[10:11], v95 offset0:146 offset1:154
	ds_read2_b32 v[12:13], v95 offset0:211 offset1:219
	ds_read2_b32 v[14:15], v24 offset0:20 offset1:28
	ds_read2_b32 v[16:17], v24 offset0:85 offset1:93
	ds_read2_b32 v[18:19], v24 offset0:150 offset1:158
	ds_read2_b32 v[22:23], v24 offset0:215 offset1:223
	v_lshl_add_u64 v[4:5], v[20:21], 0, v[144:145]
	global_store_dwordx4 v[4:5], v[0:3], off nt
	v_or_b32_e32 v4, s8, v97
	v_lshlrev_b32_e32 v144, 12, v4
	v_lshl_add_u64 v[4:5], v[20:21], 0, v[144:145]
	s_waitcnt lgkmcnt(6)
	v_cvt_pk_bf16_f32 v0, v6, v8
	s_waitcnt lgkmcnt(4)
	v_cvt_pk_bf16_f32 v1, v10, v12
	s_waitcnt lgkmcnt(2)
	v_cvt_pk_bf16_f32 v2, v14, v16
	s_waitcnt lgkmcnt(0)
	v_cvt_pk_bf16_f32 v3, v18, v22
	global_store_dwordx4 v[4:5], v[0:3], off nt
	v_or_b32_e32 v4, s8, v98
	v_lshlrev_b32_e32 v144, 12, v4
	v_cvt_pk_bf16_f32 v0, v7, v9
	v_cvt_pk_bf16_f32 v1, v11, v13
	v_cvt_pk_bf16_f32 v2, v15, v17
	v_cvt_pk_bf16_f32 v3, v19, v23
	ds_read2_b32 v[6:7], v95 offset0:32 offset1:40
	ds_read2_b32 v[8:9], v95 offset0:97 offset1:105
	ds_read2_b32 v[10:11], v95 offset0:162 offset1:170
	ds_read2_b32 v[12:13], v95 offset0:227 offset1:235
	ds_read2_b32 v[14:15], v24 offset0:36 offset1:44
	ds_read2_b32 v[16:17], v24 offset0:101 offset1:109
	ds_read2_b32 v[18:19], v24 offset0:166 offset1:174
	ds_read2_b32 v[22:23], v24 offset0:231 offset1:239
	v_lshl_add_u64 v[4:5], v[20:21], 0, v[144:145]
	global_store_dwordx4 v[4:5], v[0:3], off nt
	v_or_b32_e32 v4, s8, v99
	v_lshlrev_b32_e32 v144, 12, v4
	v_lshl_add_u64 v[4:5], v[20:21], 0, v[144:145]
	s_waitcnt lgkmcnt(6)
	v_cvt_pk_bf16_f32 v0, v6, v8
	s_waitcnt lgkmcnt(4)
	v_cvt_pk_bf16_f32 v1, v10, v12
	s_waitcnt lgkmcnt(2)
	v_cvt_pk_bf16_f32 v2, v14, v16
	s_waitcnt lgkmcnt(0)
	v_cvt_pk_bf16_f32 v3, v18, v22
	global_store_dwordx4 v[4:5], v[0:3], off nt
	v_or_b32_e32 v4, s8, v100
	v_lshlrev_b32_e32 v144, 12, v4
	v_cvt_pk_bf16_f32 v0, v7, v9
	v_cvt_pk_bf16_f32 v1, v11, v13
	v_cvt_pk_bf16_f32 v2, v15, v17
	v_cvt_pk_bf16_f32 v3, v19, v23
	ds_read2_b32 v[6:7], v95 offset0:48 offset1:56
	ds_read2_b32 v[8:9], v95 offset0:113 offset1:121
	ds_read2_b32 v[10:11], v95 offset0:178 offset1:186
	ds_read2_b32 v[12:13], v95 offset0:243 offset1:251
	ds_read2_b32 v[14:15], v24 offset0:52 offset1:60
	ds_read2_b32 v[16:17], v24 offset0:117 offset1:125
	ds_read2_b32 v[18:19], v24 offset0:182 offset1:190
	ds_read2_b32 v[22:23], v24 offset0:247 offset1:255
	v_lshl_add_u64 v[4:5], v[20:21], 0, v[144:145]
	global_store_dwordx4 v[4:5], v[0:3], off nt
	v_or_b32_e32 v4, s8, v101
	v_lshlrev_b32_e32 v144, 12, v4
	v_lshl_add_u64 v[4:5], v[20:21], 0, v[144:145]
	s_waitcnt lgkmcnt(6)
	v_cvt_pk_bf16_f32 v0, v6, v8
	s_waitcnt lgkmcnt(4)
	v_cvt_pk_bf16_f32 v1, v10, v12
	s_waitcnt lgkmcnt(2)
	v_cvt_pk_bf16_f32 v2, v14, v16
	s_waitcnt lgkmcnt(0)
	v_cvt_pk_bf16_f32 v3, v18, v22
	global_store_dwordx4 v[4:5], v[0:3], off nt
	v_or_b32_e32 v4, s8, v102
	v_lshlrev_b32_e32 v144, 12, v4
	v_lshl_add_u64 v[4:5], v[20:21], 0, v[144:145]
	v_cvt_pk_bf16_f32 v0, v7, v9
	v_cvt_pk_bf16_f32 v1, v11, v13
	v_cvt_pk_bf16_f32 v2, v15, v17
	v_cvt_pk_bf16_f32 v3, v19, v23
	global_store_dwordx4 v[4:5], v[0:3], off nt

; #define LAS __attribute__((address_space(3)))
; __device__ __forceinline__ unsigned pk2(float lo, float hi) { unsigned r; asm("v_cvt_pk_bf16_f32 %0, %1, %2" : "=v"(r) : "v"(lo), "v"(hi)); return r; }
; __device__ __forceinline__ void transpose_item(const float* W, int K, int N, bf16_t* WT, int kb, int nbd, int src0, LAS float* scr, int lane, const float* gk = nullptr) {
;     ...
;         LAS float* s = scr + (4 * i + (lane >> 4)) * 65 + (lane & 15) * 4; s[0] = v[i].x; s[1] = v[i].y; s[2] = v[i].z; s[3] = v[i].w; }
;     const int c = lane & 7;
; #pragma unroll
;     for (int jj = 0; jj < 8; ++jj) {
;         const int n = (lane >> 3) + 8 * jj; const LAS float* s = scr + (8 * c) * 65 + n;
;         u32x4 o; o.x = pk2(s[0], s[65]); o.y = pk2(s[2 * 65], s[3 * 65]); o.z = pk2(s[4 * 65], s[5 * 65]); o.w = pk2(s[6 * 65], s[7 * 65]);
;         *(u32x4*)(WT + (size_t)(nbd * 64 + n) * K + k0 + 8 * c) = o;
;     }
.LBB0_302:
	s_waitcnt vmcnt(1)
	v_add_u32_e32 v0, 0x38e0, v93
	ds_write2_b32 v0, v14, v15 offset1:1
	v_add_u32_e32 v0, 0x38e8, v93
	ds_write2_b32 v0, v12, v13 offset1:1
	v_add_u32_e32 v0, 0x3cf0, v93
	ds_write2_b32 v0, v8, v9 offset1:1
	v_add_u32_e32 v0, 0x3cf8, v93
	ds_write2_b32 v0, v10, v11 offset1:1
	s_waitcnt vmcnt(0)
	ds_read2_b32 v[6:7], v95 offset0:65 offset1:73
	ds_read2_b32 v[8:9], v95 offset1:8
	v_add_u32_e32 v24, 0x400, v95
	ds_read2_b32 v[10:11], v95 offset0:130 offset1:138
	ds_read2_b32 v[12:13], v95 offset0:195 offset1:203
	ds_read2_b32 v[14:15], v24 offset0:4 offset1:12
	ds_read2_b32 v[16:17], v24 offset0:69 offset1:77
	ds_read2_b32 v[18:19], v24 offset0:134 offset1:142
	ds_read2_b32 v[20:21], v24 offset0:199 offset1:207
	s_and_b32 s6, 0xffff, s8
	s_lshl_b32 s74, s6, 1
	s_waitcnt lgkmcnt(6)
	v_cvt_pk_bf16_f32 v2, v8, v6
	v_or_b32_e32 v6, s29, v94
	v_lshl_add_u64 v[0:1], v[76:77], 0, s[74:75]
	v_lshlrev_b32_e32 v144, 12, v6
	v_or_b32_e32 v6, s29, v96
	v_lshl_add_u64 v[22:23], v[0:1], 0, v[144:145]
	v_lshlrev_b32_e32 v144, 12, v6
	s_waitcnt lgkmcnt(4)
	v_cvt_pk_bf16_f32 v3, v10, v12
	s_waitcnt lgkmcnt(2)
	v_cvt_pk_bf16_f32 v4, v14, v16
	s_waitcnt lgkmcnt(0)
	v_cvt_pk_bf16_f32 v5, v18, v20
	global_store_dwordx4 v[22:23], v[2:5], off nt
	s_nop 1
	v_cvt_pk_bf16_f32 v2, v9, v7
	v_lshl_add_u64 v[6:7], v[0:1], 0, v[144:145]
	v_cvt_pk_bf16_f32 v3, v11, v13
	v_cvt_pk_bf16_f32 v4, v15, v17
	v_cvt_pk_bf16_f32 v5, v19, v21
	global_store_dwordx4 v[6:7], v[2:5], off nt
	ds_read2_b32 v[6:7], v95 offset0:16 offset1:24
	ds_read2_b32 v[8:9], v95 offset0:81 offset1:89
	ds_read2_b32 v[10:11], v95 offset0:146 offset1:154
	ds_read2_b32 v[12:13], v95 offset0:211 offset1:219
	ds_read2_b32 v[14:15], v24 offset0:20 offset1:28
	ds_read2_b32 v[16:17], v24 offset0:85 offset1:93
	ds_read2_b32 v[18:19], v24 offset0:150 offset1:158
	ds_read2_b32 v[20:21], v24 offset0:215 offset1:223
	s_waitcnt lgkmcnt(6)
	v_cvt_pk_bf16_f32 v2, v6, v8
	v_or_b32_e32 v6, s29, v97
	v_lshlrev_b32_e32 v144, 12, v6
	v_or_b32_e32 v6, s29, v98
	v_lshl_add_u64 v[22:23], v[0:1], 0, v[144:145]
	v_lshlrev_b32_e32 v144, 12, v6
	s_waitcnt lgkmcnt(4)
	v_cvt_pk_bf16_f32 v3, v10, v12
	s_waitcnt lgkmcnt(2)
	v_cvt_pk_bf16_f32 v4, v14, v16
	s_waitcnt lgkmcnt(0)
	v_cvt_pk_bf16_f32 v5, v18, v20
	global_store_dwordx4 v[22:23], v[2:5], off nt
	s_nop 1
	v_cvt_pk_bf16_f32 v2, v7, v9
	v_lshl_add_u64 v[6:7], v[0:1], 0, v[144:145]
	v_cvt_pk_bf16_f32 v3, v11, v13
	v_cvt_pk_bf16_f32 v4, v15, v17
	v_cvt_pk_bf16_f32 v5, v19, v21
	global_store_dwordx4 v[6:7], v[2:5], off nt
	ds_read2_b32 v[6:7], v95 offset0:32 offset1:40
	ds_read2_b32 v[8:9], v95 offset0:97 offset1:105
	ds_read2_b32 v[10:11], v95 offset0:162 offset1:170
	ds_read2_b32 v[12:13], v95 offset0:227 offset1:235
	ds_read2_b32 v[14:15], v24 offset0:36 offset1:44
	ds_read2_b32 v[16:17], v24 offset0:101 offset1:109
	ds_read2_b32 v[18:19], v24 offset0:166 offset1:174
	ds_read2_b32 v[20:21], v24 offset0:231 offset1:239
	s_waitcnt lgkmcnt(6)
	v_cvt_pk_bf16_f32 v2, v6, v8
	v_or_b32_e32 v6, s29, v99
	v_lshlrev_b32_e32 v144, 12, v6
	v_or_b32_e32 v6, s29, v100
	v_lshl_add_u64 v[22:23], v[0:1], 0, v[144:145]
	v_lshlrev_b32_e32 v144, 12, v6
	s_waitcnt lgkmcnt(4)
	v_cvt_pk_bf16_f32 v3, v10, v12
	s_waitcnt lgkmcnt(2)
	v_cvt_pk_bf16_f32 v4, v14, v16
	s_waitcnt lgkmcnt(0)
	v_cvt_pk_bf16_f32 v5, v18, v20
	global_store_dwordx4 v[22:23], v[2:5], off nt
	s_nop 1
	v_cvt_pk_bf16_f32 v2, v7, v9
	v_lshl_add_u64 v[6:7], v[0:1], 0, v[144:145]
	v_cvt_pk_bf16_f32 v3, v11, v13
	v_cvt_pk_bf16_f32 v4, v15, v17
	v_cvt_pk_bf16_f32 v5, v19, v21
	global_store_dwordx4 v[6:7], v[2:5], off nt
	ds_read2_b32 v[6:7], v95 offset0:48 offset1:56
	ds_read2_b32 v[8:9], v95 offset0:113 offset1:121
	ds_read2_b32 v[10:11], v95 offset0:178 offset1:186
	ds_read2_b32 v[12:13], v95 offset0:243 offset1:251
	ds_read2_b32 v[14:15], v24 offset0:52 offset1:60
	ds_read2_b32 v[16:17], v24 offset0:117 offset1:125
	ds_read2_b32 v[18:19], v24 offset0:182 offset1:190
	ds_read2_b32 v[20:21], v24 offset0:247 offset1:255
	s_waitcnt lgkmcnt(6)
	v_cvt_pk_bf16_f32 v2, v6, v8
	v_or_b32_e32 v6, s29, v101
	v_lshlrev_b32_e32 v144, 12, v6
	v_or_b32_e32 v6, s29, v102
	v_lshl_add_u64 v[22:23], v[0:1], 0, v[144:145]
	v_lshlrev_b32_e32 v144, 12, v6
	s_waitcnt lgkmcnt(4)
	v_cvt_pk_bf16_f32 v3, v10, v12
	s_waitcnt lgkmcnt(2)
	v_cvt_pk_bf16_f32 v4, v14, v16
	s_waitcnt lgkmcnt(0)
	v_cvt_pk_bf16_f32 v5, v18, v20
	v_lshl_add_u64 v[0:1], v[0:1], 0, v[144:145]
	global_store_dwordx4 v[22:23], v[2:5], off nt
	s_nop 1
	v_cvt_pk_bf16_f32 v2, v7, v9
	v_cvt_pk_bf16_f32 v3, v11, v13
	v_cvt_pk_bf16_f32 v4, v15, v17
	v_cvt_pk_bf16_f32 v5, v19, v21
	global_store_dwordx4 v[0:1], v[2:5], off nt

; #define LAS __attribute__((address_space(3)))
; #define SCHED_FENCE() __builtin_amdgcn_sched_barrier(0)
; __device__ __forceinline__ void transpose_item(const float* W, int K, int N, bf16_t* WT, int kb, int nbd, int src0, LAS float* scr, int lane, const float* gk = nullptr) {
;     const int k0 = kb * 64;
;     const float* wp = W + (size_t)(k0 + (lane >> 4)) * N + src0 + (lane & 15) * 4;
;     f32x4 v[16];
; #pragma unroll
;     for (int i = 0; i < 16; ++i) v[i] = *(const f32x4*)(wp + (size_t)(4 * i) * N);
;     SCHED_FENCE();
; #pragma unroll
;     for (int i = 0; i < 16; ++i) { if (gk) v[i] = v[i] * gk[k0 + 4 * i + (lane >> 4)];
;         LAS float* s = scr + (4 * i + (lane >> 4)) * 65 + (lane & 15) * 4; s[0] = v[i].x; s[1] = v[i].y; s[2] = v[i].z; s[3] = v[i].w; }
.LBB0_304:
	s_andn2_b64 vcc, exec, s[6:7]
	s_cbranch_vccnz .LBB0_306
	s_load_dwordx2 s[30:31], s[40:41], 0xb0
	s_and_b32 s6, s13, 0xffc0
	s_addk_i32 s6, 0x9200
	v_or_b32_e32 v144, s6, v92
	s_and_b32 s8, s23, 0x7c0
	v_lshlrev_b64 v[0:1], 13, v[144:145]
	s_waitcnt lgkmcnt(0)
	v_lshl_add_u64 v[0:1], s[30:31], 0, v[0:1]
	s_lshl_b32 s74, s8, 2
	v_lshl_add_u64 v[0:1], v[0:1], 0, s[74:75]
	v_lshlrev_b32_e32 v144, 2, v70
	v_lshl_add_u64 v[56:57], v[0:1], 0, v[144:145]
	v_add_co_u32_e32 v4, vcc, 0x8000, v56
	s_mov_b32 s0, 0x18000
	s_nop 0
	v_addc_co_u32_e32 v5, vcc, 0, v57, vcc
	v_add_co_u32_e32 v8, vcc, s47, v56
	global_load_dwordx4 v[0:3], v[56:57], off nt
	s_nop 0
	global_load_dwordx4 v[4:7], v[4:5], off nt
	v_addc_co_u32_e32 v9, vcc, 0, v57, vcc
	v_add_co_u32_e32 v12, vcc, s0, v56
	s_mov_b32 s0, 0x48000
	s_nop 0
	v_addc_co_u32_e32 v13, vcc, 0, v57, vcc
	v_add_co_u32_e32 v16, vcc, 0x20000, v56
	global_load_dwordx4 v[8:11], v[8:9], off nt
	s_nop 0
	global_load_dwordx4 v[12:15], v[12:13], off nt
	v_addc_co_u32_e32 v17, vcc, 0, v57, vcc
	v_add_co_u32_e32 v20, vcc, 0x28000, v56
	s_nop 1
	v_addc_co_u32_e32 v21, vcc, 0, v57, vcc
	v_add_co_u32_e32 v24, vcc, s3, v56
	global_load_dwordx4 v[16:19], v[16:17], off nt
	s_nop 0
	global_load_dwordx4 v[20:23], v[20:21], off nt
	v_addc_co_u32_e32 v25, vcc, 0, v57, vcc
	v_add_co_u32_e32 v28, vcc, 0x38000, v56
	s_nop 1
	v_addc_co_u32_e32 v29, vcc, 0, v57, vcc
	v_add_co_u32_e32 v32, vcc, s21, v56
	global_load_dwordx4 v[24:27], v[24:25], off nt
	s_nop 0
	global_load_dwordx4 v[28:31], v[28:29], off nt
	v_addc_co_u32_e32 v33, vcc, 0, v57, vcc
	v_add_co_u32_e32 v36, vcc, s0, v56
	s_mov_b32 s0, 0x58000
	s_nop 0
	v_addc_co_u32_e32 v37, vcc, 0, v57, vcc
	v_add_co_u32_e32 v40, vcc, s20, v56
	global_load_dwordx4 v[32:35], v[32:33], off nt
	s_nop 0
	global_load_dwordx4 v[36:39], v[36:37], off nt
	v_addc_co_u32_e32 v41, vcc, 0, v57, vcc
	v_add_co_u32_e32 v44, vcc, s0, v56
	s_mov_b32 s0, 0x68000
	s_nop 0
	v_addc_co_u32_e32 v45, vcc, 0, v57, vcc
	v_add_co_u32_e32 v48, vcc, s26, v56
	global_load_dwordx4 v[40:43], v[40:41], off nt
	s_nop 0
	global_load_dwordx4 v[44:47], v[44:45], off nt
	v_addc_co_u32_e32 v49, vcc, 0, v57, vcc
	v_add_co_u32_e32 v52, vcc, s0, v56
	s_mov_b32 s0, 0x78000
	s_nop 0
	v_addc_co_u32_e32 v53, vcc, 0, v57, vcc
	v_add_co_u32_e32 v58, vcc, s48, v56
	global_load_dwordx4 v[48:51], v[48:49], off nt
	s_nop 0
	global_load_dwordx4 v[52:55], v[52:53], off nt
	v_addc_co_u32_e32 v59, vcc, 0, v57, vcc
	v_add_co_u32_e32 v60, vcc, s0, v56
	s_nop 1
	v_addc_co_u32_e32 v61, vcc, 0, v57, vcc
	global_load_dwordx4 v[56:59], v[58:59], off nt
	s_nop 0
	global_load_dwordx4 v[60:63], v[60:61], off nt
	s_waitcnt vmcnt(15)
	ds_write2_b32 v93, v0, v1 offset1:1
	ds_write2_b32 v93, v2, v3 offset0:2 offset1:3
	v_add_u32_e32 v0, 0x410, v93
	s_waitcnt vmcnt(14)
	ds_write2_b32 v0, v4, v5 offset1:1
	v_add_u32_e32 v0, 0x418, v93
	ds_write2_b32 v0, v6, v7 offset1:1
	v_add_u32_e32 v0, 0x820, v93
	s_waitcnt vmcnt(13)
	ds_write2_b32 v0, v8, v9 offset1:1
	v_add_u32_e32 v0, 0x828, v93
	ds_write2_b32 v0, v10, v11 offset1:1
	v_add_u32_e32 v0, 0xc30, v93
	s_waitcnt vmcnt(12)
	ds_write2_b32 v0, v12, v13 offset1:1
	v_add_u32_e32 v0, 0xc38, v93
	ds_write2_b32 v0, v14, v15 offset1:1
	v_add_u32_e32 v0, 0x1040, v93
	s_waitcnt vmcnt(11)
	ds_write2_b32 v0, v16, v17 offset1:1
	v_add_u32_e32 v0, 0x1048, v93
	ds_write2_b32 v0, v18, v19 offset1:1
	v_add_u32_e32 v0, 0x1450, v93
	s_waitcnt vmcnt(10)
	ds_write2_b32 v0, v20, v21 offset1:1
	v_add_u32_e32 v0, 0x1458, v93
	ds_write2_b32 v0, v22, v23 offset1:1
	v_add_u32_e32 v0, 0x1860, v93
	s_waitcnt vmcnt(9)
	ds_write2_b32 v0, v24, v25 offset1:1
	v_add_u32_e32 v0, 0x1868, v93
	ds_write2_b32 v0, v26, v27 offset1:1
	v_add_u32_e32 v0, 0x1c70, v93
	s_waitcnt vmcnt(8)
	ds_write2_b32 v0, v28, v29 offset1:1
	v_add_u32_e32 v0, 0x1c78, v93
	ds_write2_b32 v0, v30, v31 offset1:1
	v_add_u32_e32 v0, 0x2080, v93
	s_waitcnt vmcnt(7)
	ds_write2_b32 v0, v32, v33 offset1:1
	v_add_u32_e32 v0, 0x2088, v93
	ds_write2_b32 v0, v34, v35 offset1:1
	v_add_u32_e32 v0, 0x2490, v93
	s_waitcnt vmcnt(6)
	ds_write2_b32 v0, v36, v37 offset1:1
	v_add_u32_e32 v0, 0x2498, v93
	ds_write2_b32 v0, v38, v39 offset1:1
	v_add_u32_e32 v0, 0x28a0, v93
	s_waitcnt vmcnt(5)
	ds_write2_b32 v0, v40, v41 offset1:1
	v_add_u32_e32 v0, 0x28a8, v93
	ds_write2_b32 v0, v42, v43 offset1:1
	v_add_u32_e32 v0, 0x2cb0, v93
	s_waitcnt vmcnt(4)
	ds_write2_b32 v0, v44, v45 offset1:1
	v_add_u32_e32 v0, 0x2cb8, v93
	ds_write2_b32 v0, v46, v47 offset1:1
	v_add_u32_e32 v0, 0x30c0, v93
	s_waitcnt vmcnt(3)
	ds_write2_b32 v0, v48, v49 offset1:1
	v_add_u32_e32 v0, 0x30c8, v93
	ds_write2_b32 v0, v50, v51 offset1:1
	v_add_u32_e32 v0, 0x34d0, v93
	s_waitcnt vmcnt(2)
	ds_write2_b32 v0, v52, v53 offset1:1
	v_add_u32_e32 v0, 0x34d8, v93
	ds_write2_b32 v0, v54, v55 offset1:1
	v_add_u32_e32 v0, 0x38e0, v93
	s_waitcnt vmcnt(1)
; #define LAS __attribute__((address_space(3)))
; __device__ __forceinline__ unsigned pk2(float lo, float hi) { unsigned r; asm("v_cvt_pk_bf16_f32 %0, %1, %2" : "=v"(r) : "v"(lo), "v"(hi)); return r; }
; __device__ __forceinline__ void transpose_item(const float* W, int K, int N, bf16_t* WT, int kb, int nbd, int src0, LAS float* scr, int lane, const float* gk = nullptr) {
;     ...
;     const int c = lane & 7;
; #pragma unroll
;     for (int jj = 0; jj < 8; ++jj) {
;         const int n = (lane >> 3) + 8 * jj; const LAS float* s = scr + (8 * c) * 65 + n;
;         u32x4 o; o.x = pk2(s[0], s[65]); o.y = pk2(s[2 * 65], s[3 * 65]); o.z = pk2(s[4 * 65], s[5 * 65]); o.w = pk2(s[6 * 65], s[7 * 65]);
;         *(u32x4*)(WT + (size_t)(nbd * 64 + n) * K + k0 + 8 * c) = o;
;     }
	ds_write2_b32 v0, v56, v57 offset1:1
	v_add_u32_e32 v0, 0x38e8, v93
	ds_write2_b32 v0, v58, v59 offset1:1
	v_add_u32_e32 v0, 0x3cf0, v93
	s_waitcnt vmcnt(0)
	ds_write2_b32 v0, v60, v61 offset1:1
	v_add_u32_e32 v0, 0x3cf8, v93
	ds_write2_b32 v0, v62, v63 offset1:1
	ds_read2_b32 v[4:5], v95 offset0:65 offset1:73
	ds_read2_b32 v[6:7], v95 offset1:8
	ds_read2_b32 v[8:9], v95 offset0:130 offset1:138
	ds_read2_b32 v[10:11], v95 offset0:195 offset1:203
	v_add_u32_e32 v24, 0x400, v95
	ds_read2_b32 v[12:13], v24 offset0:4 offset1:12
	ds_read2_b32 v[14:15], v24 offset0:69 offset1:77
	ds_read2_b32 v[16:17], v24 offset0:134 offset1:142
	ds_read2_b32 v[18:19], v24 offset0:199 offset1:207
	s_waitcnt lgkmcnt(6)
	v_cvt_pk_bf16_f32 v0, v6, v4
	v_or_b32_e32 v4, s8, v94
	s_mov_b32 s7, s75
	v_mul_u32_u24_e32 v4, 0x1600, v4
	v_lshl_add_u64 v[20:21], s[6:7], 1, v[78:79]
	v_lshlrev_b32_e32 v144, 1, v4
	v_or_b32_e32 v4, s8, v96
	v_lshl_add_u64 v[22:23], v[20:21], 0, v[144:145]
	v_mul_u32_u24_e32 v4, 0x1600, v4
	s_waitcnt lgkmcnt(4)
	v_cvt_pk_bf16_f32 v1, v8, v10
	s_waitcnt lgkmcnt(2)
	v_cvt_pk_bf16_f32 v2, v12, v14
	s_waitcnt lgkmcnt(0)
	v_cvt_pk_bf16_f32 v3, v16, v18
	global_store_dwordx4 v[22:23], v[0:3], off nt
	v_lshlrev_b32_e32 v144, 1, v4
	s_nop 0
	v_cvt_pk_bf16_f32 v0, v7, v5
	v_cvt_pk_bf16_f32 v1, v9, v11
	v_cvt_pk_bf16_f32 v2, v13, v15
	v_cvt_pk_bf16_f32 v3, v17, v19
	v_lshl_add_u64 v[4:5], v[20:21], 0, v[144:145]
	ds_read2_b32 v[6:7], v95 offset0:16 offset1:24
	ds_read2_b32 v[8:9], v95 offset0:81 offset1:89
	ds_read2_b32 v[10:11], v95 offset0:146 offset1:154
	ds_read2_b32 v[12:13], v95 offset0:211 offset1:219
	ds_read2_b32 v[14:15], v24 offset0:20 offset1:28
	ds_read2_b32 v[16:17], v24 offset0:85 offset1:93
	ds_read2_b32 v[18:19], v24 offset0:150 offset1:158
	ds_read2_b32 v[22:23], v24 offset0:215 offset1:223
	global_store_dwordx4 v[4:5], v[0:3], off nt
	v_or_b32_e32 v4, s8, v97
	v_mul_u32_u24_e32 v4, 0x1600, v4
	v_lshlrev_b32_e32 v144, 1, v4
	v_lshl_add_u64 v[4:5], v[20:21], 0, v[144:145]
	s_waitcnt lgkmcnt(6)
	v_cvt_pk_bf16_f32 v0, v6, v8
	s_waitcnt lgkmcnt(4)
	v_cvt_pk_bf16_f32 v1, v10, v12
	s_waitcnt lgkmcnt(2)
	v_cvt_pk_bf16_f32 v2, v14, v16
	s_waitcnt lgkmcnt(0)
	v_cvt_pk_bf16_f32 v3, v18, v22
	global_store_dwordx4 v[4:5], v[0:3], off nt
	v_or_b32_e32 v4, s8, v98
	v_mul_u32_u24_e32 v4, 0x1600, v4
	v_lshlrev_b32_e32 v144, 1, v4
	v_cvt_pk_bf16_f32 v0, v7, v9
	v_cvt_pk_bf16_f32 v1, v11, v13
	v_cvt_pk_bf16_f32 v2, v15, v17
	v_cvt_pk_bf16_f32 v3, v19, v23
	v_lshl_add_u64 v[4:5], v[20:21], 0, v[144:145]
	ds_read2_b32 v[6:7], v95 offset0:32 offset1:40
	ds_read2_b32 v[8:9], v95 offset0:97 offset1:105
	ds_read2_b32 v[10:11], v95 offset0:162 offset1:170
	ds_read2_b32 v[12:13], v95 offset0:227 offset1:235
	ds_read2_b32 v[14:15], v24 offset0:36 offset1:44
	ds_read2_b32 v[16:17], v24 offset0:101 offset1:109
	ds_read2_b32 v[18:19], v24 offset0:166 offset1:174
	ds_read2_b32 v[22:23], v24 offset0:231 offset1:239
	global_store_dwordx4 v[4:5], v[0:3], off nt
	v_or_b32_e32 v4, s8, v99
	v_mul_u32_u24_e32 v4, 0x1600, v4
	v_lshlrev_b32_e32 v144, 1, v4
	v_lshl_add_u64 v[4:5], v[20:21], 0, v[144:145]
	s_waitcnt lgkmcnt(6)
	v_cvt_pk_bf16_f32 v0, v6, v8
	s_waitcnt lgkmcnt(4)
	v_cvt_pk_bf16_f32 v1, v10, v12
	s_waitcnt lgkmcnt(2)
	v_cvt_pk_bf16_f32 v2, v14, v16
	s_waitcnt lgkmcnt(0)
	v_cvt_pk_bf16_f32 v3, v18, v22
	global_store_dwordx4 v[4:5], v[0:3], off nt
	v_or_b32_e32 v4, s8, v100
	v_mul_u32_u24_e32 v4, 0x1600, v4
	v_lshlrev_b32_e32 v144, 1, v4
	v_cvt_pk_bf16_f32 v0, v7, v9
	v_cvt_pk_bf16_f32 v1, v11, v13
	v_cvt_pk_bf16_f32 v2, v15, v17
	v_cvt_pk_bf16_f32 v3, v19, v23
	v_lshl_add_u64 v[4:5], v[20:21], 0, v[144:145]
	ds_read2_b32 v[6:7], v95 offset0:48 offset1:56
	ds_read2_b32 v[8:9], v95 offset0:113 offset1:121
	ds_read2_b32 v[10:11], v95 offset0:178 offset1:186
	ds_read2_b32 v[12:13], v95 offset0:243 offset1:251
	ds_read2_b32 v[14:15], v24 offset0:52 offset1:60
	ds_read2_b32 v[16:17], v24 offset0:117 offset1:125
	ds_read2_b32 v[18:19], v24 offset0:182 offset1:190
	ds_read2_b32 v[22:23], v24 offset0:247 offset1:255
	global_store_dwordx4 v[4:5], v[0:3], off nt
	v_or_b32_e32 v4, s8, v101
	v_mul_u32_u24_e32 v4, 0x1600, v4
	v_lshlrev_b32_e32 v144, 1, v4
	v_lshl_add_u64 v[4:5], v[20:21], 0, v[144:145]
	s_waitcnt lgkmcnt(6)
	v_cvt_pk_bf16_f32 v0, v6, v8
	s_waitcnt lgkmcnt(4)
	v_cvt_pk_bf16_f32 v1, v10, v12
	s_waitcnt lgkmcnt(2)
	v_cvt_pk_bf16_f32 v2, v14, v16
	s_waitcnt lgkmcnt(0)
	v_cvt_pk_bf16_f32 v3, v18, v22
	global_store_dwordx4 v[4:5], v[0:3], off nt
	v_or_b32_e32 v4, s8, v102
	v_mul_u32_u24_e32 v4, 0x1600, v4
	v_lshlrev_b32_e32 v144, 1, v4
	v_lshl_add_u64 v[4:5], v[20:21], 0, v[144:145]
	v_cvt_pk_bf16_f32 v0, v7, v9
	v_cvt_pk_bf16_f32 v1, v11, v13
	v_cvt_pk_bf16_f32 v2, v15, v17
	v_cvt_pk_bf16_f32 v3, v19, v23
	global_store_dwordx4 v[4:5], v[0:3], off nt

; #define LAS __attribute__((address_space(3)))
; __device__ __forceinline__ unsigned pk2(float lo, float hi) { unsigned r; asm("v_cvt_pk_bf16_f32 %0, %1, %2" : "=v"(r) : "v"(lo), "v"(hi)); return r; }
; __device__ __forceinline__ void transpose_item(const float* W, int K, int N, bf16_t* WT, int kb, int nbd, int src0, LAS float* scr, int lane, const float* gk = nullptr) {
;     ...
;         LAS float* s = scr + (4 * i + (lane >> 4)) * 65 + (lane & 15) * 4; s[0] = v[i].x; s[1] = v[i].y; s[2] = v[i].z; s[3] = v[i].w; }
;     const int c = lane & 7;
; #pragma unroll
;     for (int jj = 0; jj < 8; ++jj) {
;         const int n = (lane >> 3) + 8 * jj; const LAS float* s = scr + (8 * c) * 65 + n;
;         u32x4 o; o.x = pk2(s[0], s[65]); o.y = pk2(s[2 * 65], s[3 * 65]); o.z = pk2(s[4 * 65], s[5 * 65]); o.w = pk2(s[6 * 65], s[7 * 65]);
;         *(u32x4*)(WT + (size_t)(nbd * 64 + n) * K + k0 + 8 * c) = o;
;     }
.LBB0_335:
	s_waitcnt vmcnt(1)
	v_add_u32_e32 v0, 0x38e0, v93
	ds_write2_b32 v0, v14, v15 offset1:1
	v_add_u32_e32 v0, 0x38e8, v93
	ds_write2_b32 v0, v12, v13 offset1:1
	v_add_u32_e32 v0, 0x3cf0, v93
	ds_write2_b32 v0, v8, v9 offset1:1
	v_add_u32_e32 v0, 0x3cf8, v93
	ds_write2_b32 v0, v10, v11 offset1:1
	s_waitcnt vmcnt(0)
	ds_read2_b32 v[6:7], v95 offset0:65 offset1:73
	ds_read2_b32 v[8:9], v95 offset1:8
	v_add_u32_e32 v24, 0x400, v95
	ds_read2_b32 v[10:11], v95 offset0:130 offset1:138
	ds_read2_b32 v[12:13], v95 offset0:195 offset1:203
	ds_read2_b32 v[14:15], v24 offset0:4 offset1:12
	ds_read2_b32 v[16:17], v24 offset0:69 offset1:77
	ds_read2_b32 v[18:19], v24 offset0:134 offset1:142
	ds_read2_b32 v[20:21], v24 offset0:199 offset1:207
	s_lshl_b32 s6, s8, 6
	s_and_b32 s7, 0xffff, s9
	s_lshl_b32 s74, s7, 1
	s_waitcnt lgkmcnt(6)
	v_cvt_pk_bf16_f32 v2, v8, v6
	v_or_b32_e32 v6, s6, v94
	v_lshl_add_u64 v[0:1], v[82:83], 0, s[74:75]
	v_lshlrev_b32_e32 v144, 12, v6
	v_or_b32_e32 v6, s6, v96
	v_lshl_add_u64 v[22:23], v[0:1], 0, v[144:145]
	v_lshlrev_b32_e32 v144, 12, v6
	s_waitcnt lgkmcnt(4)
	v_cvt_pk_bf16_f32 v3, v10, v12
	s_waitcnt lgkmcnt(2)
	v_cvt_pk_bf16_f32 v4, v14, v16
	s_waitcnt lgkmcnt(0)
	v_cvt_pk_bf16_f32 v5, v18, v20
	global_store_dwordx4 v[22:23], v[2:5], off nt
	s_nop 1
	v_cvt_pk_bf16_f32 v2, v9, v7
	v_lshl_add_u64 v[6:7], v[0:1], 0, v[144:145]
	v_cvt_pk_bf16_f32 v3, v11, v13
	v_cvt_pk_bf16_f32 v4, v15, v17
	v_cvt_pk_bf16_f32 v5, v19, v21
	global_store_dwordx4 v[6:7], v[2:5], off nt
	ds_read2_b32 v[6:7], v95 offset0:16 offset1:24
	ds_read2_b32 v[8:9], v95 offset0:81 offset1:89
	ds_read2_b32 v[10:11], v95 offset0:146 offset1:154
	ds_read2_b32 v[12:13], v95 offset0:211 offset1:219
	ds_read2_b32 v[14:15], v24 offset0:20 offset1:28
	ds_read2_b32 v[16:17], v24 offset0:85 offset1:93
	ds_read2_b32 v[18:19], v24 offset0:150 offset1:158
	ds_read2_b32 v[20:21], v24 offset0:215 offset1:223
	s_waitcnt lgkmcnt(6)
	v_cvt_pk_bf16_f32 v2, v6, v8
	v_or_b32_e32 v6, s6, v97
	v_lshlrev_b32_e32 v144, 12, v6
	v_or_b32_e32 v6, s6, v98
	v_lshl_add_u64 v[22:23], v[0:1], 0, v[144:145]
	v_lshlrev_b32_e32 v144, 12, v6
	s_waitcnt lgkmcnt(4)
	v_cvt_pk_bf16_f32 v3, v10, v12
	s_waitcnt lgkmcnt(2)
	v_cvt_pk_bf16_f32 v4, v14, v16
	s_waitcnt lgkmcnt(0)
	v_cvt_pk_bf16_f32 v5, v18, v20
	global_store_dwordx4 v[22:23], v[2:5], off nt
	s_nop 1
	v_cvt_pk_bf16_f32 v2, v7, v9
	v_lshl_add_u64 v[6:7], v[0:1], 0, v[144:145]
	v_cvt_pk_bf16_f32 v3, v11, v13
	v_cvt_pk_bf16_f32 v4, v15, v17
	v_cvt_pk_bf16_f32 v5, v19, v21
	global_store_dwordx4 v[6:7], v[2:5], off nt
	ds_read2_b32 v[6:7], v95 offset0:32 offset1:40
	ds_read2_b32 v[8:9], v95 offset0:97 offset1:105
	ds_read2_b32 v[10:11], v95 offset0:162 offset1:170
	ds_read2_b32 v[12:13], v95 offset0:227 offset1:235
	ds_read2_b32 v[14:15], v24 offset0:36 offset1:44
	ds_read2_b32 v[16:17], v24 offset0:101 offset1:109
	ds_read2_b32 v[18:19], v24 offset0:166 offset1:174
	ds_read2_b32 v[20:21], v24 offset0:231 offset1:239
	s_waitcnt lgkmcnt(6)
	v_cvt_pk_bf16_f32 v2, v6, v8
	v_or_b32_e32 v6, s6, v99
	v_lshlrev_b32_e32 v144, 12, v6
	v_or_b32_e32 v6, s6, v100
	v_lshl_add_u64 v[22:23], v[0:1], 0, v[144:145]
	v_lshlrev_b32_e32 v144, 12, v6
	s_waitcnt lgkmcnt(4)
	v_cvt_pk_bf16_f32 v3, v10, v12
	s_waitcnt lgkmcnt(2)
	v_cvt_pk_bf16_f32 v4, v14, v16
	s_waitcnt lgkmcnt(0)
	v_cvt_pk_bf16_f32 v5, v18, v20
	global_store_dwordx4 v[22:23], v[2:5], off nt
	s_nop 1
	v_cvt_pk_bf16_f32 v2, v7, v9
	v_lshl_add_u64 v[6:7], v[0:1], 0, v[144:145]
	v_cvt_pk_bf16_f32 v3, v11, v13
	v_cvt_pk_bf16_f32 v4, v15, v17
	v_cvt_pk_bf16_f32 v5, v19, v21
	global_store_dwordx4 v[6:7], v[2:5], off nt
	ds_read2_b32 v[6:7], v95 offset0:48 offset1:56
	ds_read2_b32 v[8:9], v95 offset0:113 offset1:121
	ds_read2_b32 v[10:11], v95 offset0:178 offset1:186
	ds_read2_b32 v[12:13], v95 offset0:243 offset1:251
	ds_read2_b32 v[14:15], v24 offset0:52 offset1:60
	ds_read2_b32 v[16:17], v24 offset0:117 offset1:125
	ds_read2_b32 v[18:19], v24 offset0:182 offset1:190
	ds_read2_b32 v[20:21], v24 offset0:247 offset1:255
	s_waitcnt lgkmcnt(6)
	v_cvt_pk_bf16_f32 v2, v6, v8
	v_or_b32_e32 v6, s6, v101
	v_lshlrev_b32_e32 v144, 12, v6
	v_or_b32_e32 v6, s6, v102
	v_lshl_add_u64 v[22:23], v[0:1], 0, v[144:145]
	v_lshlrev_b32_e32 v144, 12, v6
	s_waitcnt lgkmcnt(4)
	v_cvt_pk_bf16_f32 v3, v10, v12
	s_waitcnt lgkmcnt(2)
	v_cvt_pk_bf16_f32 v4, v14, v16
	s_waitcnt lgkmcnt(0)
	v_cvt_pk_bf16_f32 v5, v18, v20
	v_lshl_add_u64 v[0:1], v[0:1], 0, v[144:145]
	global_store_dwordx4 v[22:23], v[2:5], off nt
	s_nop 1
	v_cvt_pk_bf16_f32 v2, v7, v9
	v_cvt_pk_bf16_f32 v3, v11, v13
	v_cvt_pk_bf16_f32 v4, v15, v17
	v_cvt_pk_bf16_f32 v5, v19, v21
	global_store_dwordx4 v[0:1], v[2:5], off nt
